# ML consumer: V prefetch waited once before register rotation instead of conservative in-iteration vmcnt waits
# speedup vs baseline: 1.0029x; 1.0029x over previous
; template <bool CONS>
; DI void ml_chain_role(const Params& p, unsigned char* smem, int dir, int b, int h) {
;     ...
;     float mstate = 0.f;
;     if (tid0 < 128) ((float*)(smem + LSM) + 448)[tid0] = 0.f;
;     u32x4 pq[4], pk[4]; float pig = 0.f, pfr = 0.f; int prow = 0;
;     unsigned short pvv[2][2][8];
;     if (!CONS) {
; #pragma unroll
;         for (int it = 0; it < 4; ++it) {
;             const int idx = tid0 - 256 + 256 * it, i = idx >> 4, c8 = idx & 15;
;             const bf16_t* src = P + (size_t)scan_row(1, dir, b, 0, 0, i) * P2W + 512 + h * 128 + c8 * 8;
;             pq[it] = *(const u32x4*)src; pk[it] = *(const u32x4*)(src + 512);
;         }
;         if (wave == 5) { prow = scan_row(1, dir, b, 0, 0, lane0); pig = graw[(size_t)prow * 32 + 16 + dir * 4 + h]; pfr = graw[(size_t)prow * 32 + 24 + dir * 4 + h]; }
;     } else {
; #pragma unroll
;         for (int ci = 0; ci < 2; ++ci)
; #pragma unroll
;             for (int s = 0; s < 2; ++s)
; #pragma unroll
;                 for (int e = 0; e < 8; ++e) { const int row = scan_row(1, dir, b, 0, 0, 32 * ci + 16 * s + 8 * (lane0 >> 5) + e);
;                     pvv[ci][s][e] = P[(size_t)row * P2W + 512 + 1024 + h * 128 + 32 * wave + (lane0 & 31)]; }
.LBB0_475:
	s_and_b64 vcc, exec, s[4:5]
	s_cbranch_vccz .LBB0_494
	s_movk_i32 s4, 0x80
	v_readfirstlane_b32 s8, v180
	v_cmp_gt_u32_e32 vcc, s4, v180
	s_and_saveexec_b64 s[4:5], vcc
	v_lshl_add_u32 v0, v180, 2, 0
	v_add_u32_e32 v0, 0x24b00, v0
	v_mov_b32_e32 v1, 0
	ds_write_b32 v0, v1
	s_or_b64 exec, exec, s[4:5]
	s_add_u32 s6, s30, 0x1ef76000
	s_addc_u32 s7, s31, 0
	s_lshl_b32 s4, s42, 27
	s_add_u32 s4, s30, s4
	s_addc_u32 s5, s31, 0
	s_add_u32 s12, s4, 0x2376000
	s_addc_u32 s13, s5, 0
	s_waitcnt vmcnt(0)
	v_lshrrev_b32_e32 v18, 2, v180
	v_and_b32_e32 v19, 8, v18
	s_cmp_eq_u32 s42, 0
	s_movk_i32 s4, 0xff
	v_and_b32_e32 v4, 31, v180
	s_movk_i32 s18, 0xfe
	v_bitop3_b32 v0, v18, s4, 8 bitop3:0x6c
	s_cselect_b64 s[4:5], -1, 0
	s_lshl_b32 s22, s43, 8
	v_lshlrev_b32_e32 v112, 1, v4
	v_or_b32_e32 v4, 1, v19
	v_bitop3_b32 v5, v18, s18, 8 bitop3:0x6c
	s_add_i32 s22, s22, 0x10000
	v_cndmask_b32_e64 v0, v0, v19, s[4:5]
	v_cndmask_b32_e64 v4, v5, v4, s[4:5]
	s_waitcnt lgkmcnt(0)
	v_or_b32_e32 v2, s22, v0
	s_movk_i32 s17, 0x1400
	v_mov_b64_e32 v[0:1], s[6:7]
	v_or_b32_e32 v4, s22, v4
	v_mad_i64_i32 v[4:5], s[18:19], v4, s17, v[0:1]
	s_movk_i32 s18, 0xfd
	v_or_b32_e32 v6, 2, v19
	v_bitop3_b32 v7, v18, s18, 8 bitop3:0x6c
	v_cndmask_b32_e64 v6, v7, v6, s[4:5]
	v_or_b32_e32 v6, s22, v6
	v_mad_i64_i32 v[6:7], s[18:19], v6, s17, v[0:1]
	s_movk_i32 s18, 0xfc
	v_or_b32_e32 v8, 3, v19
	v_bitop3_b32 v9, v18, s18, 8 bitop3:0x6c
	v_cndmask_b32_e64 v8, v9, v8, s[4:5]
	v_or_b32_e32 v8, s22, v8
	v_mad_i64_i32 v[8:9], s[18:19], v8, s17, v[0:1]
	s_movk_i32 s18, 0xfb
	v_or_b32_e32 v10, 4, v19
	v_bitop3_b32 v11, v18, s18, 8 bitop3:0x6c
	v_cndmask_b32_e64 v10, v11, v10, s[4:5]
	v_or_b32_e32 v10, s22, v10
	v_mad_i64_i32 v[10:11], s[18:19], v10, s17, v[0:1]
	s_movk_i32 s18, 0xfa
	v_or_b32_e32 v12, 5, v19
	v_bitop3_b32 v13, v18, s18, 8 bitop3:0x6c
	v_cndmask_b32_e64 v12, v13, v12, s[4:5]
	v_or_b32_e32 v12, s22, v12
	v_mad_i64_i32 v[12:13], s[18:19], v12, s17, v[0:1]
	s_movk_i32 s18, 0xf9
	v_or_b32_e32 v14, 6, v19
	v_bitop3_b32 v15, v18, s18, 8 bitop3:0x6c
	v_cndmask_b32_e64 v14, v15, v14, s[4:5]
	v_or_b32_e32 v14, s22, v14
	v_mad_i64_i32 v[14:15], s[18:19], v14, s17, v[0:1]
	s_movk_i32 s18, 0xf8
	v_or_b32_e32 v16, 7, v19
	v_bitop3_b32 v17, v18, s18, 8 bitop3:0x6c
	s_lshr_b32 s8, s8, 1
	v_cndmask_b32_e64 v16, v17, v16, s[4:5]
	s_mov_b32 s9, 0
	s_and_b32 s16, s8, 0x7fffffe0
	v_mad_i64_i32 v[2:3], s[14:15], v2, s17, v[0:1]
	s_lshl_b32 s8, s3, 8
	v_or_b32_e32 v16, s22, v16
	v_lshl_add_u64 v[2:3], v[2:3], 0, s[8:9]
	s_lshl_b32 s14, s16, 1
	s_mov_b32 s15, s9
	v_mad_i64_i32 v[16:17], s[18:19], v16, s17, v[0:1]
	v_lshl_add_u64 v[2:3], v[2:3], 0, s[14:15]
	v_mov_b32_e32 v113, 0
	v_lshl_add_u64 v[4:5], v[4:5], 0, s[8:9]
	v_lshl_add_u64 v[6:7], v[6:7], 0, s[8:9]
	v_lshl_add_u64 v[8:9], v[8:9], 0, s[8:9]
	v_lshl_add_u64 v[10:11], v[10:11], 0, s[8:9]
	v_lshl_add_u64 v[12:13], v[12:13], 0, s[8:9]
	v_lshl_add_u64 v[14:15], v[14:15], 0, s[8:9]
	v_lshl_add_u64 v[16:17], v[16:17], 0, s[8:9]
	v_lshl_add_u64 v[2:3], v[2:3], 0, v[112:113]
	v_lshl_add_u64 v[4:5], v[4:5], 0, s[14:15]
	v_lshl_add_u64 v[6:7], v[6:7], 0, s[14:15]
	v_lshl_add_u64 v[8:9], v[8:9], 0, s[14:15]
	v_lshl_add_u64 v[10:11], v[10:11], 0, s[14:15]
	v_lshl_add_u64 v[12:13], v[12:13], 0, s[14:15]
	v_lshl_add_u64 v[14:15], v[14:15], 0, s[14:15]
	v_lshl_add_u64 v[16:17], v[16:17], 0, s[14:15]
	s_movk_i32 s18, 0xef
	v_lshl_add_u64 v[4:5], v[4:5], 0, v[112:113]
	v_lshl_add_u64 v[6:7], v[6:7], 0, v[112:113]
	v_lshl_add_u64 v[8:9], v[8:9], 0, v[112:113]
	v_lshl_add_u64 v[10:11], v[10:11], 0, v[112:113]
	v_lshl_add_u64 v[12:13], v[12:13], 0, v[112:113]
	v_lshl_add_u64 v[14:15], v[14:15], 0, v[112:113]
	v_lshl_add_u64 v[16:17], v[16:17], 0, v[112:113]
	global_load_ushort v108, v[2:3], off offset:3072
	global_load_ushort v96, v[4:5], off offset:3072
	global_load_ushort v109, v[6:7], off offset:3072
	global_load_ushort v97, v[8:9], off offset:3072
	global_load_ushort v110, v[10:11], off offset:3072
	global_load_ushort v98, v[12:13], off offset:3072
	global_load_ushort v111, v[14:15], off offset:3072
	global_load_ushort v99, v[16:17], off offset:3072
	v_or_b32_e32 v2, 16, v19
	v_bitop3_b32 v3, v18, s18, 8 bitop3:0x6c
	v_cndmask_b32_e64 v2, v3, v2, s[4:5]
	v_or_b32_e32 v2, s22, v2
	v_mad_i64_i32 v[2:3], s[18:19], v2, s17, v[0:1]
	s_movk_i32 s18, 0xee
	v_or_b32_e32 v4, 17, v19
	v_bitop3_b32 v5, v18, s18, 8 bitop3:0x6c
	v_cndmask_b32_e64 v4, v5, v4, s[4:5]
	v_or_b32_e32 v4, s22, v4
	v_mad_i64_i32 v[4:5], s[18:19], v4, s17, v[0:1]
	s_movk_i32 s18, 0xed
	v_or_b32_e32 v6, 18, v19
	v_bitop3_b32 v7, v18, s18, 8 bitop3:0x6c
	v_cndmask_b32_e64 v6, v7, v6, s[4:5]
	v_or_b32_e32 v6, s22, v6
	v_mad_i64_i32 v[6:7], s[18:19], v6, s17, v[0:1]
	s_movk_i32 s18, 0xec
	v_or_b32_e32 v8, 19, v19
	v_bitop3_b32 v9, v18, s18, 8 bitop3:0x6c
	v_cndmask_b32_e64 v8, v9, v8, s[4:5]
	v_or_b32_e32 v8, s22, v8
	v_mad_i64_i32 v[8:9], s[18:19], v8, s17, v[0:1]
	s_movk_i32 s18, 0xeb
	v_or_b32_e32 v10, 20, v19
	v_bitop3_b32 v11, v18, s18, 8 bitop3:0x6c
	v_cndmask_b32_e64 v10, v11, v10, s[4:5]
	v_or_b32_e32 v10, s22, v10
	v_mad_i64_i32 v[10:11], s[18:19], v10, s17, v[0:1]
	s_movk_i32 s18, 0xea
	v_or_b32_e32 v12, 21, v19
	v_bitop3_b32 v13, v18, s18, 8 bitop3:0x6c
	v_cndmask_b32_e64 v12, v13, v12, s[4:5]
	v_or_b32_e32 v12, s22, v12
	v_mad_i64_i32 v[12:13], s[18:19], v12, s17, v[0:1]
	s_movk_i32 s18, 0xe9
	v_or_b32_e32 v14, 22, v19
	v_bitop3_b32 v15, v18, s18, 8 bitop3:0x6c
	v_cndmask_b32_e64 v14, v15, v14, s[4:5]
	v_or_b32_e32 v14, s22, v14
	v_mad_i64_i32 v[14:15], s[18:19], v14, s17, v[0:1]
	s_movk_i32 s18, 0xe8
	v_or_b32_e32 v16, 23, v19
	v_bitop3_b32 v17, v18, s18, 8 bitop3:0x6c
; template <bool CONS>
; DI void ml_chain_role(const Params& p, unsigned char* smem, int dir, int b, int h) {
;     ...
; #pragma unroll
;         for (int ci = 0; ci < 2; ++ci)
; #pragma unroll
;             for (int s = 0; s < 2; ++s)
; #pragma unroll
;                 for (int e = 0; e < 8; ++e) { const int row = scan_row(1, dir, b, 0, 0, 32 * ci + 16 * s + 8 * (lane0 >> 5) + e);
;                     pvv[ci][s][e] = P[(size_t)row * P2W + 512 + 1024 + h * 128 + 32 * wave + (lane0 & 31)]; }
	v_cndmask_b32_e64 v16, v17, v16, s[4:5]
	v_or_b32_e32 v16, s22, v16
	v_lshl_add_u64 v[2:3], v[2:3], 0, s[8:9]
	v_mad_i64_i32 v[16:17], s[18:19], v16, s17, v[0:1]
	v_lshl_add_u64 v[2:3], v[2:3], 0, s[14:15]
	v_lshl_add_u64 v[4:5], v[4:5], 0, s[8:9]
	v_lshl_add_u64 v[6:7], v[6:7], 0, s[8:9]
	v_lshl_add_u64 v[8:9], v[8:9], 0, s[8:9]
	v_lshl_add_u64 v[10:11], v[10:11], 0, s[8:9]
	v_lshl_add_u64 v[12:13], v[12:13], 0, s[8:9]
	v_lshl_add_u64 v[14:15], v[14:15], 0, s[8:9]
	v_lshl_add_u64 v[16:17], v[16:17], 0, s[8:9]
	v_lshl_add_u64 v[2:3], v[2:3], 0, v[112:113]
	v_lshl_add_u64 v[4:5], v[4:5], 0, s[14:15]
	v_lshl_add_u64 v[6:7], v[6:7], 0, s[14:15]
	v_lshl_add_u64 v[8:9], v[8:9], 0, s[14:15]
	v_lshl_add_u64 v[10:11], v[10:11], 0, s[14:15]
	v_lshl_add_u64 v[12:13], v[12:13], 0, s[14:15]
	v_lshl_add_u64 v[14:15], v[14:15], 0, s[14:15]
	v_lshl_add_u64 v[16:17], v[16:17], 0, s[14:15]
	s_movk_i32 s18, 0xdf
	v_lshl_add_u64 v[4:5], v[4:5], 0, v[112:113]
	v_lshl_add_u64 v[6:7], v[6:7], 0, v[112:113]
	v_lshl_add_u64 v[8:9], v[8:9], 0, v[112:113]
	v_lshl_add_u64 v[10:11], v[10:11], 0, v[112:113]
	v_lshl_add_u64 v[12:13], v[12:13], 0, v[112:113]
	v_lshl_add_u64 v[14:15], v[14:15], 0, v[112:113]
	v_lshl_add_u64 v[16:17], v[16:17], 0, v[112:113]
	global_load_ushort v101, v[2:3], off offset:3072
	global_load_ushort v100, v[4:5], off offset:3072
	global_load_ushort v103, v[6:7], off offset:3072
	global_load_ushort v102, v[8:9], off offset:3072
	global_load_ushort v105, v[10:11], off offset:3072
	global_load_ushort v104, v[12:13], off offset:3072
	global_load_ushort v107, v[14:15], off offset:3072
	global_load_ushort v106, v[16:17], off offset:3072
	v_or_b32_e32 v2, 32, v19
	v_bitop3_b32 v3, v18, s18, 8 bitop3:0x6c
	v_cndmask_b32_e64 v2, v3, v2, s[4:5]
	v_or_b32_e32 v2, s22, v2
	v_mad_i64_i32 v[2:3], s[18:19], v2, s17, v[0:1]
	s_movk_i32 s18, 0xde
	v_or_b32_e32 v4, 33, v19
	v_bitop3_b32 v5, v18, s18, 8 bitop3:0x6c
	v_cndmask_b32_e64 v4, v5, v4, s[4:5]
	v_or_b32_e32 v4, s22, v4
	v_mad_i64_i32 v[4:5], s[18:19], v4, s17, v[0:1]
	s_movk_i32 s18, 0xdd
	v_or_b32_e32 v6, 34, v19
	v_bitop3_b32 v7, v18, s18, 8 bitop3:0x6c
	v_cndmask_b32_e64 v6, v7, v6, s[4:5]
	v_or_b32_e32 v6, s22, v6
	v_mad_i64_i32 v[6:7], s[18:19], v6, s17, v[0:1]
	s_movk_i32 s18, 0xdc
	v_or_b32_e32 v8, 35, v19
	v_bitop3_b32 v9, v18, s18, 8 bitop3:0x6c
	v_cndmask_b32_e64 v8, v9, v8, s[4:5]
	v_or_b32_e32 v8, s22, v8
	v_mad_i64_i32 v[8:9], s[18:19], v8, s17, v[0:1]
	s_movk_i32 s18, 0xdb
	v_or_b32_e32 v10, 36, v19
	v_bitop3_b32 v11, v18, s18, 8 bitop3:0x6c
	v_cndmask_b32_e64 v10, v11, v10, s[4:5]
	v_or_b32_e32 v10, s22, v10
	v_mad_i64_i32 v[10:11], s[18:19], v10, s17, v[0:1]
	s_movk_i32 s18, 0xda
	v_or_b32_e32 v12, 37, v19
	v_bitop3_b32 v13, v18, s18, 8 bitop3:0x6c
	v_cndmask_b32_e64 v12, v13, v12, s[4:5]
	v_or_b32_e32 v12, s22, v12
	v_mad_i64_i32 v[12:13], s[18:19], v12, s17, v[0:1]
	s_movk_i32 s18, 0xd9
	v_or_b32_e32 v14, 38, v19
	v_bitop3_b32 v15, v18, s18, 8 bitop3:0x6c
	v_cndmask_b32_e64 v14, v15, v14, s[4:5]
	v_or_b32_e32 v14, s22, v14
	v_mad_i64_i32 v[14:15], s[18:19], v14, s17, v[0:1]
	s_movk_i32 s18, 0xd8
	v_or_b32_e32 v16, 39, v19
	v_bitop3_b32 v17, v18, s18, 8 bitop3:0x6c
	v_cndmask_b32_e64 v16, v17, v16, s[4:5]
	v_or_b32_e32 v16, s22, v16
	v_lshl_add_u64 v[2:3], v[2:3], 0, s[8:9]
	v_mad_i64_i32 v[16:17], s[18:19], v16, s17, v[0:1]
	v_lshl_add_u64 v[2:3], v[2:3], 0, s[14:15]
	v_lshl_add_u64 v[4:5], v[4:5], 0, s[8:9]
	v_lshl_add_u64 v[6:7], v[6:7], 0, s[8:9]
	v_lshl_add_u64 v[8:9], v[8:9], 0, s[8:9]
	v_lshl_add_u64 v[10:11], v[10:11], 0, s[8:9]
	v_lshl_add_u64 v[12:13], v[12:13], 0, s[8:9]
	v_lshl_add_u64 v[14:15], v[14:15], 0, s[8:9]
	v_lshl_add_u64 v[16:17], v[16:17], 0, s[8:9]
	v_lshl_add_u64 v[2:3], v[2:3], 0, v[112:113]
	v_lshl_add_u64 v[4:5], v[4:5], 0, s[14:15]
	v_lshl_add_u64 v[6:7], v[6:7], 0, s[14:15]
	v_lshl_add_u64 v[8:9], v[8:9], 0, s[14:15]
	v_lshl_add_u64 v[10:11], v[10:11], 0, s[14:15]
	v_lshl_add_u64 v[12:13], v[12:13], 0, s[14:15]
	v_lshl_add_u64 v[14:15], v[14:15], 0, s[14:15]
	v_lshl_add_u64 v[16:17], v[16:17], 0, s[14:15]
	s_movk_i32 s18, 0xcf
	v_lshl_add_u64 v[4:5], v[4:5], 0, v[112:113]
	v_lshl_add_u64 v[6:7], v[6:7], 0, v[112:113]
	v_lshl_add_u64 v[8:9], v[8:9], 0, v[112:113]
	v_lshl_add_u64 v[10:11], v[10:11], 0, v[112:113]
	v_lshl_add_u64 v[12:13], v[12:13], 0, v[112:113]
	v_lshl_add_u64 v[14:15], v[14:15], 0, v[112:113]
	v_lshl_add_u64 v[16:17], v[16:17], 0, v[112:113]
	global_load_ushort v150, v[2:3], off offset:3072
	global_load_ushort v114, v[4:5], off offset:3072
	global_load_ushort v152, v[6:7], off offset:3072
	global_load_ushort v151, v[8:9], off offset:3072
	global_load_ushort v154, v[10:11], off offset:3072
	global_load_ushort v153, v[12:13], off offset:3072
	global_load_ushort v156, v[14:15], off offset:3072
	global_load_ushort v155, v[16:17], off offset:3072
	v_or_b32_e32 v2, 48, v19
	v_bitop3_b32 v3, v18, s18, 8 bitop3:0x6c
	v_cndmask_b32_e64 v2, v3, v2, s[4:5]
	v_or_b32_e32 v2, s22, v2
	v_mad_i64_i32 v[2:3], s[18:19], v2, s17, v[0:1]
	s_movk_i32 s18, 0xce
	v_or_b32_e32 v4, 49, v19
	v_bitop3_b32 v5, v18, s18, 8 bitop3:0x6c
	v_cndmask_b32_e64 v4, v5, v4, s[4:5]
	v_or_b32_e32 v4, s22, v4
	v_mad_i64_i32 v[4:5], s[18:19], v4, s17, v[0:1]
	s_movk_i32 s18, 0xcd
	v_or_b32_e32 v6, 50, v19
	v_bitop3_b32 v7, v18, s18, 8 bitop3:0x6c
	v_cndmask_b32_e64 v6, v7, v6, s[4:5]
	v_or_b32_e32 v6, s22, v6
	v_mad_i64_i32 v[6:7], s[18:19], v6, s17, v[0:1]
	s_movk_i32 s18, 0xcc
	v_or_b32_e32 v8, 51, v19
	v_bitop3_b32 v9, v18, s18, 8 bitop3:0x6c
	v_cndmask_b32_e64 v8, v9, v8, s[4:5]
	v_or_b32_e32 v8, s22, v8
	v_mad_i64_i32 v[8:9], s[18:19], v8, s17, v[0:1]
	s_movk_i32 s18, 0xcb
; template <bool CONS>
; DI void ml_chain_role(const Params& p, unsigned char* smem, int dir, int b, int h) {
;     ...
;     if (CONS) {
; #pragma unroll
;         for (int kt = 0; kt < 4; ++kt) for (int i = 0; i < 16; ++i) C[kt][i] = 0.f;
;     }
;     float mstate = 0.f;
;     if (tid0 < 128) ((float*)(smem + LSM) + 448)[tid0] = 0.f;
;     u32x4 pq[4], pk[4]; float pig = 0.f, pfr = 0.f; int prow = 0;
;     unsigned short pvv[2][2][8];
;     if (!CONS) {
; #pragma unroll
;         for (int it = 0; it < 4; ++it) {
;             const int idx = tid0 - 256 + 256 * it, i = idx >> 4, c8 = idx & 15;
;             const bf16_t* src = P + (size_t)scan_row(1, dir, b, 0, 0, i) * P2W + 512 + h * 128 + c8 * 8;
;             pq[it] = *(const u32x4*)src; pk[it] = *(const u32x4*)(src + 512);
;         }
;         if (wave == 5) { prow = scan_row(1, dir, b, 0, 0, lane0); pig = graw[(size_t)prow * 32 + 16 + dir * 4 + h]; pfr = graw[(size_t)prow * 32 + 24 + dir * 4 + h]; }
;     } else {
; #pragma unroll
;         for (int ci = 0; ci < 2; ++ci)
; #pragma unroll
;             for (int s = 0; s < 2; ++s)
; #pragma unroll
;                 for (int e = 0; e < 8; ++e) { const int row = scan_row(1, dir, b, 0, 0, 32 * ci + 16 * s + 8 * (lane0 >> 5) + e);
;                     pvv[ci][s][e] = P[(size_t)row * P2W + 512 + 1024 + h * 128 + 32 * wave + (lane0 & 31)]; }
;     }
;     __syncthreads();
	v_or_b32_e32 v10, 52, v19
	v_bitop3_b32 v11, v18, s18, 8 bitop3:0x6c
	v_cndmask_b32_e64 v10, v11, v10, s[4:5]
	v_or_b32_e32 v10, s22, v10
	v_mad_i64_i32 v[10:11], s[18:19], v10, s17, v[0:1]
	s_movk_i32 s18, 0xca
	v_or_b32_e32 v12, 53, v19
	v_bitop3_b32 v13, v18, s18, 8 bitop3:0x6c
	v_cndmask_b32_e64 v12, v13, v12, s[4:5]
	v_or_b32_e32 v12, s22, v12
	v_mad_i64_i32 v[12:13], s[18:19], v12, s17, v[0:1]
	s_movk_i32 s18, 0xc9
	v_or_b32_e32 v14, 54, v19
	v_bitop3_b32 v15, v18, s18, 8 bitop3:0x6c
	v_cndmask_b32_e64 v14, v15, v14, s[4:5]
	v_or_b32_e32 v14, s22, v14
	v_mad_i64_i32 v[14:15], s[18:19], v14, s17, v[0:1]
	s_movk_i32 s18, 0xc8
	v_or_b32_e32 v16, 55, v19
	v_bitop3_b32 v17, v18, s18, 8 bitop3:0x6c
	v_cndmask_b32_e64 v16, v17, v16, s[4:5]
	v_or_b32_e32 v16, s22, v16
	v_lshl_add_u64 v[2:3], v[2:3], 0, s[8:9]
	v_mad_i64_i32 v[0:1], s[18:19], v16, s17, v[0:1]
	v_lshl_add_u64 v[2:3], v[2:3], 0, s[14:15]
	v_lshl_add_u64 v[4:5], v[4:5], 0, s[8:9]
	v_lshl_add_u64 v[6:7], v[6:7], 0, s[8:9]
	v_lshl_add_u64 v[8:9], v[8:9], 0, s[8:9]
	v_lshl_add_u64 v[10:11], v[10:11], 0, s[8:9]
	v_lshl_add_u64 v[12:13], v[12:13], 0, s[8:9]
	v_lshl_add_u64 v[14:15], v[14:15], 0, s[8:9]
	v_lshl_add_u64 v[0:1], v[0:1], 0, s[8:9]
	v_lshl_add_u64 v[2:3], v[2:3], 0, v[112:113]
	v_lshl_add_u64 v[4:5], v[4:5], 0, s[14:15]
	v_lshl_add_u64 v[6:7], v[6:7], 0, s[14:15]
	v_lshl_add_u64 v[8:9], v[8:9], 0, s[14:15]
	v_lshl_add_u64 v[10:11], v[10:11], 0, s[14:15]
	v_lshl_add_u64 v[12:13], v[12:13], 0, s[14:15]
	v_lshl_add_u64 v[14:15], v[14:15], 0, s[14:15]
	v_lshl_add_u64 v[0:1], v[0:1], 0, s[14:15]
	v_lshl_add_u64 v[4:5], v[4:5], 0, v[112:113]
	v_lshl_add_u64 v[6:7], v[6:7], 0, v[112:113]
	v_lshl_add_u64 v[8:9], v[8:9], 0, v[112:113]
	v_lshl_add_u64 v[10:11], v[10:11], 0, v[112:113]
	v_lshl_add_u64 v[12:13], v[12:13], 0, v[112:113]
	v_lshl_add_u64 v[14:15], v[14:15], 0, v[112:113]
	v_lshl_add_u64 v[0:1], v[0:1], 0, v[112:113]
	global_load_ushort v158, v[2:3], off offset:3072
	global_load_ushort v157, v[4:5], off offset:3072
	global_load_ushort v160, v[6:7], off offset:3072
	global_load_ushort v159, v[8:9], off offset:3072
	global_load_ushort v162, v[10:11], off offset:3072
	global_load_ushort v161, v[12:13], off offset:3072
	global_load_ushort v164, v[14:15], off offset:3072
	global_load_ushort v163, v[0:1], off offset:3072
	s_lshl_b32 s23, s3, 7
	s_add_i32 s23, s23, s16
	v_and_b32_e32 v115, 63, v180
	s_lshl_b32 s8, s43, 12
	s_add_i32 s24, s23, 0x200
	s_mov_b32 s25, -3
	s_add_i32 s38, 0, 0x15800
	s_mov_b32 s39, 0x5040100
	s_add_i32 s40, 0, 0x11000
	v_mov_b32_e32 v116, 0x1400
	v_mov_b32_e32 v117, 0xb400
	v_mov_b32_e32 v0, v113
	v_mov_b32_e32 v1, v113
	v_mov_b32_e32 v2, v113
	v_mov_b32_e32 v3, v113
	v_mov_b32_e32 v4, v113
	v_mov_b32_e32 v5, v113
	v_mov_b32_e32 v6, v113
	v_mov_b32_e32 v7, v113
	v_mov_b32_e32 v8, v113
	v_mov_b32_e32 v9, v113
	v_mov_b32_e32 v10, v113
	v_mov_b32_e32 v11, v113
	v_mov_b32_e32 v12, v113
	v_mov_b32_e32 v13, v113
	v_mov_b32_e32 v14, v113
	v_mov_b32_e32 v15, v113
	v_mov_b32_e32 v16, v113
	v_mov_b32_e32 v17, v113
	v_mov_b32_e32 v18, v113
	v_mov_b32_e32 v19, v113
	v_mov_b32_e32 v20, v113
	v_mov_b32_e32 v21, v113
	v_mov_b32_e32 v22, v113
	v_mov_b32_e32 v23, v113
	v_mov_b32_e32 v24, v113
	v_mov_b32_e32 v25, v113
	v_mov_b32_e32 v26, v113
	v_mov_b32_e32 v27, v113
	v_mov_b32_e32 v28, v113
	v_mov_b32_e32 v29, v113
	v_mov_b32_e32 v30, v113
	v_mov_b32_e32 v31, v113
	v_mov_b32_e32 v32, v113
	v_mov_b32_e32 v33, v113
	v_mov_b32_e32 v34, v113
	v_mov_b32_e32 v35, v113
	v_mov_b32_e32 v36, v113
	v_mov_b32_e32 v37, v113
	v_mov_b32_e32 v38, v113
	v_mov_b32_e32 v39, v113
	v_mov_b32_e32 v40, v113
	v_mov_b32_e32 v41, v113
	v_mov_b32_e32 v42, v113
	v_mov_b32_e32 v43, v113
	v_mov_b32_e32 v44, v113
	v_mov_b32_e32 v45, v113
	v_mov_b32_e32 v46, v113
	v_mov_b32_e32 v47, v113
	v_mov_b32_e32 v48, v113
	v_mov_b32_e32 v49, v113
	v_mov_b32_e32 v50, v113
	v_mov_b32_e32 v51, v113
	v_mov_b32_e32 v52, v113
	v_mov_b32_e32 v53, v113
	v_mov_b32_e32 v54, v113
	v_mov_b32_e32 v55, v113
	v_mov_b32_e32 v56, v113
	v_mov_b32_e32 v57, v113
	v_mov_b32_e32 v58, v113
	v_mov_b32_e32 v59, v113
	v_mov_b32_e32 v60, v113
	v_mov_b32_e32 v61, v113
	v_mov_b32_e32 v62, v113
	v_mov_b32_e32 v63, v113
	s_waitcnt vmcnt(0)
	s_barrier
	s_branch .LBB0_480
; #define MFMA32(a, b, c) __builtin_amdgcn_mfma_f32_32x32x16_bf16((a), (b), (c), 0, 0, 0)
; template <bool CONS>
; DI void ml_chain_role(const Params& p, unsigned char* smem, int dir, int b, int h) {
;     ...
; #pragma unroll
;             for (int kt = 0; kt < 4; ++kt) for (int i = 0; i < 16; ++i) C[kt][i] *= cs;
; #pragma unroll
;             for (int ci = 0; ci < 2; ++ci)
; #pragma unroll
;                 for (int s = 0; s < 2; ++s)
; #pragma unroll
;                     for (int kt = 0; kt < 4; ++kt) C[kt] = MFMA32(load_nat(sKT, STT, 32 * kt + r, 32 * ci + 16 * s + 8 * hh), vf[ci][s], C[kt]);
.LBB0_479:
	s_nop 7
	v_add3_u32 v84, s40, v167, v168
	s_nop 0
	ds_read_b128 v[64:67], v84
	ds_read_b128 v[68:71], v84 offset:32
	ds_read_b128 v[72:75], v84 offset:4608
	s_waitcnt lgkmcnt(3)
	v_pk_mul_f32 v[62:63], v[62:63], v[114:115] op_sel_hi:[1,0]
	v_pk_mul_f32 v[60:61], v[60:61], v[114:115] op_sel_hi:[1,0]
	v_pk_mul_f32 v[58:59], v[58:59], v[114:115] op_sel_hi:[1,0]
	v_pk_mul_f32 v[56:57], v[56:57], v[114:115] op_sel_hi:[1,0]
	v_pk_mul_f32 v[54:55], v[54:55], v[114:115] op_sel_hi:[1,0]
	v_pk_mul_f32 v[52:53], v[52:53], v[114:115] op_sel_hi:[1,0]
	v_pk_mul_f32 v[50:51], v[50:51], v[114:115] op_sel_hi:[1,0]
	v_pk_mul_f32 v[48:49], v[48:49], v[114:115] op_sel_hi:[1,0]
	v_pk_mul_f32 v[46:47], v[46:47], v[114:115] op_sel_hi:[1,0]
	v_pk_mul_f32 v[44:45], v[44:45], v[114:115] op_sel_hi:[1,0]
	v_pk_mul_f32 v[42:43], v[42:43], v[114:115] op_sel_hi:[1,0]
	v_pk_mul_f32 v[40:41], v[40:41], v[114:115] op_sel_hi:[1,0]
	v_pk_mul_f32 v[38:39], v[38:39], v[114:115] op_sel_hi:[1,0]
	v_pk_mul_f32 v[36:37], v[36:37], v[114:115] op_sel_hi:[1,0]
	v_pk_mul_f32 v[34:35], v[34:35], v[114:115] op_sel_hi:[1,0]
	v_pk_mul_f32 v[32:33], v[32:33], v[114:115] op_sel_hi:[1,0]
	s_waitcnt lgkmcnt(2)
	v_mfma_f32_32x32x16_bf16 v[48:63], v[64:67], v[96:99], v[48:63]
	ds_read_b128 v[64:67], v84 offset:9216
	ds_read_b128 v[76:79], v84 offset:4640
	v_mul_f32_e64 v30, v30, v114
	v_mul_f32_e64 v31, v31, v114
	v_mul_f32_e64 v28, v28, v114
	v_mul_f32_e64 v29, v29, v114
	v_pk_mul_f32 v[26:27], v[26:27], v[114:115] op_sel_hi:[1,0]
	v_pk_mul_f32 v[24:25], v[24:25], v[114:115] op_sel_hi:[1,0]
	v_pk_mul_f32 v[22:23], v[22:23], v[114:115] op_sel_hi:[1,0]
	v_pk_mul_f32 v[20:21], v[20:21], v[114:115] op_sel_hi:[1,0]
	s_waitcnt lgkmcnt(2)
	v_mfma_f32_32x32x16_bf16 v[32:47], v[72:75], v[96:99], v[32:47]
	ds_read_b128 v[72:75], v84 offset:13824
	ds_read_b128 v[80:83], v84 offset:9248
	v_mul_f32_e64 v18, v18, v114
	v_mul_f32_e64 v19, v19, v114
	v_mul_f32_e64 v16, v16, v114
	v_mul_f32_e64 v17, v17, v114
	v_pk_mul_f32 v[14:15], v[14:15], v[114:115] op_sel_hi:[1,0]
	v_pk_mul_f32 v[12:13], v[12:13], v[114:115] op_sel_hi:[1,0]
	v_pk_mul_f32 v[10:11], v[10:11], v[114:115] op_sel_hi:[1,0]
	v_pk_mul_f32 v[8:9], v[8:9], v[114:115] op_sel_hi:[1,0]
	s_waitcnt lgkmcnt(3)
	v_mfma_f32_32x32x16_bf16 v[16:31], v[64:67], v[96:99], v[16:31]
	v_mul_f32_e64 v6, v6, v114
	v_mul_f32_e64 v7, v7, v114
	v_mul_f32_e64 v4, v4, v114
	v_mul_f32_e64 v5, v5, v114
	v_mul_f32_e64 v2, v2, v114
	v_mul_f32_e64 v3, v3, v114
	v_pk_mul_f32 v[0:1], v[0:1], v[114:115] op_sel_hi:[1,0]
	ds_read_b128 v[64:67], v84 offset:13856
	s_waitcnt lgkmcnt(2)
	v_mfma_f32_32x32x16_bf16 v[0:15], v[72:75], v[96:99], v[0:15]
	v_mfma_f32_32x32x16_bf16 v[48:63], v[68:71], v[104:107], v[48:63]
	v_mfma_f32_32x32x16_bf16 v[32:47], v[76:79], v[104:107], v[32:47]
	s_waitcnt lgkmcnt(0)
	v_mfma_f32_32x32x16_bf16 v[0:15], v[64:67], v[104:107], v[0:15]
	ds_read_b128 v[64:67], v84 offset:64
	ds_read_b128 v[68:71], v84 offset:96
	v_mfma_f32_32x32x16_bf16 v[16:31], v[80:83], v[104:107], v[16:31]
	s_waitcnt lgkmcnt(1)
	v_mfma_f32_32x32x16_bf16 v[48:63], v[64:67], v[100:103], v[48:63]
	ds_read_b128 v[64:67], v84 offset:4672
	ds_read_b128 v[72:75], v84 offset:4704
	s_waitcnt lgkmcnt(1)
	v_mfma_f32_32x32x16_bf16 v[32:47], v[64:67], v[100:103], v[32:47]
	ds_read_b128 v[64:67], v84 offset:9280
	ds_read_b128 v[76:79], v84 offset:9312
	s_waitcnt lgkmcnt(1)
	v_mfma_f32_32x32x16_bf16 v[16:31], v[64:67], v[100:103], v[16:31]
	ds_read_b128 v[64:67], v84 offset:13888
	ds_read_b128 v[80:83], v84 offset:13920
	s_waitcnt lgkmcnt(1)
	v_mfma_f32_32x32x16_bf16 v[0:15], v[64:67], v[100:103], v[0:15]
	v_mfma_f32_32x32x16_bf16 v[48:63], v[68:71], v[108:111], v[48:63]
	v_mfma_f32_32x32x16_bf16 v[32:47], v[72:75], v[108:111], v[32:47]
	v_mfma_f32_32x32x16_bf16 v[16:31], v[76:79], v[108:111], v[16:31]
	s_waitcnt lgkmcnt(0)
	v_mfma_f32_32x32x16_bf16 v[0:15], v[80:83], v[108:111], v[0:15]
	s_setprio 0
	s_add_i32 s25, s25, 1
	s_addk_i32 s9, 0x1000
	s_cmpk_eq_i32 s25, 0x41
	s_waitcnt vmcnt(0)
	v_mov_b32_e32 v163, v149
	v_mov_b32_e32 v164, v148
	v_mov_b32_e32 v161, v147
	v_mov_b32_e32 v162, v146
	v_mov_b32_e32 v159, v145
	v_mov_b32_e32 v160, v144
	v_mov_b32_e32 v157, v143
	v_mov_b32_e32 v158, v142
	v_mov_b32_e32 v155, v141
	v_mov_b32_e32 v156, v140
	v_mov_b32_e32 v153, v139
	v_mov_b32_e32 v154, v138
	v_mov_b32_e32 v151, v137
	v_mov_b32_e32 v152, v136
	v_mov_b32_e32 v114, v135
	v_mov_b32_e32 v150, v134
	v_mov_b32_e32 v106, v133
	v_mov_b32_e32 v107, v132
	v_mov_b32_e32 v104, v131
	v_mov_b32_e32 v105, v130
	v_mov_b32_e32 v102, v129
	v_mov_b32_e32 v103, v128
	v_mov_b32_e32 v100, v127
	v_mov_b32_e32 v101, v126
	v_mov_b32_e32 v99, v125
	v_mov_b32_e32 v111, v124
	v_mov_b32_e32 v98, v123
	v_mov_b32_e32 v110, v122
	v_mov_b32_e32 v97, v121
	v_mov_b32_e32 v109, v120
	v_mov_b32_e32 v96, v119
	v_mov_b32_e32 v108, v118
	s_cbranch_scc1 .LBB0_494

; #define MFMA32(a, b, c) __builtin_amdgcn_mfma_f32_32x32x16_bf16((a), (b), (c), 0, 0, 0)
; DI int crow(int reg, int hh) { return (reg & 3) + 8 * (reg >> 2) + 4 * hh; }
; template <bool CONS>
; DI void ml_chain_role(const Params& p, unsigned char* smem, int dir, int b, int h) {
;     ...
;                     for (int e = 0; e < 8; ++e) vf[ci][s][e] = (short)pvv[ci][s][e];
;     ...
;             for (int kt = 0; kt < 4; ++kt)
; #pragma unroll
;                 for (int s = 0; s < 2; ++s) { const bf16x8 bf = pack_step(C[kt], s);
; #pragma unroll
;                     for (int mi = 0; mi < 2; ++mi) o[mi] = MFMA32(load_perm(sQ, ST, 32 * mi + r, 32 * kt + 16 * s, hh), bf, o[mi]); }
; #pragma unroll
;             for (int mi = 0; mi < 2; ++mi)
; #pragma unroll
;                 for (int i = 0; i < 16; ++i) o[mi][i] *= sWin[32 * mi + crow(i, hh)];
;     ...
; #pragma unroll
;             for (int ci = 0; ci < 2; ++ci)
; #pragma unroll
;                 for (int s = 0; s < 2; ++s)
; #pragma unroll
;                     for (int mi = 0; mi < 2; ++mi) o[mi] = MFMA32(load_nat(sS, STT, 32 * mi + r, 32 * ci + 16 * s + 8 * hh), vf[ci][s], o[mi]);
.LBB0_492:
	v_mul_u32_u24_e32 v65, 0x110, v165
	s_waitcnt lgkmcnt(0)
	s_barrier
	v_add3_u32 v112, 0, v64, v65
	ds_read2_b64 v[64:67], v112 offset1:2
	v_cvt_pk_bf16_f32 v68, v48, v49
	v_cvt_pk_bf16_f32 v69, v50, v51
	v_cvt_pk_bf16_f32 v70, v52, v53
	v_cvt_pk_bf16_f32 v71, v54, v55
	v_add_u32_e32 v176, 0x2000, v112
	ds_read2_b64 v[168:171], v112 offset0:4 offset1:6
	s_waitcnt lgkmcnt(1)
	v_mfma_f32_32x32x16_bf16 v[80:95], v[64:67], v[68:71], 0
	ds_read2_b64 v[64:67], v176 offset0:64 offset1:66
	v_cvt_pk_bf16_f32 v172, v56, v57
	v_cvt_pk_bf16_f32 v173, v58, v59
	v_cvt_pk_bf16_f32 v174, v60, v61
	v_cvt_pk_bf16_f32 v175, v62, v63
	s_and_b32 s14, s9, 0x1000
	s_add_i32 s14, s14, 0
	s_waitcnt lgkmcnt(1)
	v_mfma_f32_32x32x16_bf16 v[80:95], v[168:171], v[172:175], v[80:95]
	ds_read2_b64 v[168:171], v176 offset0:68 offset1:70
	s_add_i32 s14, s14, 0x24400
	v_lshlrev_b32_e32 v167, 4, v167
	v_perm_b32 v99, v99, v111, s39
	v_perm_b32 v98, v98, v110, s39
	v_perm_b32 v97, v97, v109, s39
	v_perm_b32 v96, v96, v108, s39
	s_waitcnt lgkmcnt(1)
	v_mfma_f32_32x32x16_bf16 v[64:79], v[64:67], v[68:71], 0
	v_perm_b32 v107, v106, v107, s39
	v_perm_b32 v106, v104, v105, s39
	v_perm_b32 v105, v102, v103, s39
	v_perm_b32 v104, v100, v101, s39
	v_perm_b32 v103, v155, v156, s39
	v_perm_b32 v102, v153, v154, s39
	v_perm_b32 v101, v151, v152, s39
	s_waitcnt lgkmcnt(0)
	v_mfma_f32_32x32x16_bf16 v[64:79], v[168:171], v[172:175], v[64:79]
	ds_read2_b64 v[168:171], v112 offset0:8 offset1:10
	v_cvt_pk_bf16_f32 v172, v32, v33
	v_cvt_pk_bf16_f32 v173, v34, v35
	v_cvt_pk_bf16_f32 v174, v36, v37
	v_cvt_pk_bf16_f32 v175, v38, v39
	v_perm_b32 v100, v114, v150, s39
	v_cmp_gt_u32_e32 vcc, 4, v166
	s_waitcnt lgkmcnt(0)
	v_mfma_f32_32x32x16_bf16 v[80:95], v[168:171], v[172:175], v[80:95]
	ds_read2_b64 v[168:171], v176 offset0:72 offset1:74
	s_waitcnt lgkmcnt(0)
	v_mfma_f32_32x32x16_bf16 v[64:79], v[168:171], v[172:175], v[64:79]
	ds_read2_b64 v[168:171], v112 offset0:12 offset1:14
	v_cvt_pk_bf16_f32 v172, v40, v41
	v_cvt_pk_bf16_f32 v173, v42, v43
	v_cvt_pk_bf16_f32 v174, v44, v45
	v_cvt_pk_bf16_f32 v175, v46, v47
	s_waitcnt lgkmcnt(0)
	s_nop 0
	v_mfma_f32_32x32x16_bf16 v[80:95], v[168:171], v[172:175], v[80:95]
	ds_read2_b64 v[168:171], v176 offset0:76 offset1:78
	s_waitcnt lgkmcnt(0)
	v_mfma_f32_32x32x16_bf16 v[64:79], v[168:171], v[172:175], v[64:79]
	ds_read2_b64 v[168:171], v112 offset0:16 offset1:18
	v_cvt_pk_bf16_f32 v172, v16, v17
	v_cvt_pk_bf16_f32 v173, v18, v19
	v_cvt_pk_bf16_f32 v174, v20, v21
	v_cvt_pk_bf16_f32 v175, v22, v23
	s_waitcnt lgkmcnt(0)
	s_nop 0
	v_mfma_f32_32x32x16_bf16 v[80:95], v[168:171], v[172:175], v[80:95]
	ds_read2_b64 v[168:171], v176 offset0:80 offset1:82
	s_waitcnt lgkmcnt(0)
	v_mfma_f32_32x32x16_bf16 v[64:79], v[168:171], v[172:175], v[64:79]
	ds_read2_b64 v[168:171], v112 offset0:20 offset1:22
	v_cvt_pk_bf16_f32 v172, v24, v25
	v_cvt_pk_bf16_f32 v173, v26, v27
	v_cvt_pk_bf16_f32 v174, v28, v29
	v_cvt_pk_bf16_f32 v175, v30, v31
	s_waitcnt lgkmcnt(0)
	s_nop 0
	v_mfma_f32_32x32x16_bf16 v[80:95], v[168:171], v[172:175], v[80:95]
	ds_read2_b64 v[168:171], v176 offset0:84 offset1:86
	s_waitcnt lgkmcnt(0)
	v_mfma_f32_32x32x16_bf16 v[64:79], v[168:171], v[172:175], v[64:79]
	ds_read2_b64 v[168:171], v112 offset0:24 offset1:26
	v_cvt_pk_bf16_f32 v172, v0, v1
	v_cvt_pk_bf16_f32 v173, v2, v3
	v_cvt_pk_bf16_f32 v174, v4, v5
	v_cvt_pk_bf16_f32 v175, v6, v7
	s_waitcnt lgkmcnt(0)
	s_nop 0
	v_mfma_f32_32x32x16_bf16 v[80:95], v[168:171], v[172:175], v[80:95]
	ds_read2_b64 v[168:171], v176 offset0:88 offset1:90
	ds_read2_b64 v[176:179], v176 offset0:92 offset1:94
	s_waitcnt lgkmcnt(1)
	v_mfma_f32_32x32x16_bf16 v[64:79], v[168:171], v[172:175], v[64:79]
	ds_read2_b64 v[168:171], v112 offset0:28 offset1:30
	v_cvt_pk_bf16_f32 v172, v8, v9
	v_cvt_pk_bf16_f32 v173, v10, v11
	v_cvt_pk_bf16_f32 v174, v12, v13
	v_cvt_pk_bf16_f32 v175, v14, v15
	s_waitcnt lgkmcnt(0)
	s_nop 0
	v_mfma_f32_32x32x16_bf16 v[80:95], v[168:171], v[172:175], v[80:95]
	v_add_u32_e32 v169, s14, v167
	v_mul_u32_u24_e32 v168, 0x90, v165
	ds_read_b128 v[182:185], v169 offset:512
	ds_read_b128 v[186:189], v169 offset:544
	v_add3_u32 v112, s38, v167, v168
	s_waitcnt lgkmcnt(0)
	s_nop 5
	v_pk_mul_f32 v[86:87], v[86:87], v[188:189]
	v_mfma_f32_32x32x16_bf16 v[64:79], v[176:179], v[172:175], v[64:79]
	ds_read_b128 v[170:173], v169 offset:576
	ds_read_b128 v[174:177], v169 offset:608
	ds_read_b128 v[190:193], v169 offset:640
	ds_read_b128 v[194:197], v169 offset:672
	ds_read_b128 v[198:201], v169 offset:704
	ds_read_b128 v[202:205], v169 offset:736
	s_waitcnt lgkmcnt(0)
	s_barrier
	ds_read_b128 v[108:111], v112
	s_waitcnt lgkmcnt(5)
	v_pk_mul_f32 v[94:95], v[94:95], v[176:177]
	v_pk_mul_f32 v[92:93], v[92:93], v[174:175]
	v_pk_mul_f32 v[90:91], v[90:91], v[172:173]
	v_pk_mul_f32 v[88:89], v[88:89], v[170:171]
	v_pk_mul_f32 v[84:85], v[84:85], v[186:187]
	v_pk_mul_f32 v[82:83], v[82:83], v[184:185]
	v_pk_mul_f32 v[80:81], v[80:81], v[182:183]
	ds_read_b128 v[170:173], v112 offset:32
	s_waitcnt lgkmcnt(2)
	v_pk_mul_f32 v[78:79], v[78:79], v[204:205]
	s_waitcnt lgkmcnt(1)
	v_mfma_f32_32x32x16_bf16 v[80:95], v[108:111], v[96:99], v[80:95]
	ds_read_b128 v[108:111], v112 offset:4608
	ds_read_b128 v[174:177], v112 offset:4640
	v_mul_f32_e64 v76, v76, v202
	v_mul_f32_e64 v77, v77, v203
	v_mul_f32_e64 v74, v74, v200
	v_mul_f32_e64 v75, v75, v201
	v_pk_mul_f32 v[72:73], v[72:73], v[198:199]
	v_pk_mul_f32 v[70:71], v[70:71], v[196:197]
	v_pk_mul_f32 v[68:69], v[68:69], v[194:195]
	v_pk_mul_f32 v[66:67], v[66:67], v[192:193]
	v_pk_mul_f32 v[64:65], v[64:65], v[190:191]
	s_waitcnt lgkmcnt(2)
	v_mfma_f32_32x32x16_bf16 v[80:95], v[170:173], v[104:107], v[80:95]
	ds_read_b128 v[150:153], v112 offset:96
	s_waitcnt lgkmcnt(2)
	v_mfma_f32_32x32x16_bf16 v[64:79], v[108:111], v[96:99], v[64:79]
	ds_read_b128 v[108:111], v112 offset:64
	s_waitcnt lgkmcnt(2)
	v_mfma_f32_32x32x16_bf16 v[64:79], v[174:177], v[104:107], v[64:79]
	s_waitcnt lgkmcnt(0)
	v_mfma_f32_32x32x16_bf16 v[80:95], v[108:111], v[100:103], v[80:95]
	ds_read_b128 v[108:111], v112 offset:4672
	ds_read_b128 v[170:173], v112 offset:4704
	s_waitcnt lgkmcnt(0)
	s_barrier
; DI bf16_t f2bf(float a) { return (bf16_t)(pk2(a, 0.f) & 0xffffu); }
; #define MFMA32(a, b, c) __builtin_amdgcn_mfma_f32_32x32x16_bf16((a), (b), (c), 0, 0, 0)
; DI int crow(int reg, int hh) { return (reg & 3) + 8 * (reg >> 2) + 4 * hh; }
; #define LDS_BARRIER() do { asm volatile("s_waitcnt lgkmcnt(0)" ::: "memory"); __builtin_amdgcn_s_barrier(); asm volatile("" ::: "memory"); } while (0)
; template <bool CONS>
; DI void ml_chain_role(const Params& p, unsigned char* smem, int dir, int b, int h) {
;     ...
; #pragma unroll
;             for (int ci = 0; ci < 2; ++ci)
; #pragma unroll
;                 for (int s = 0; s < 2; ++s)
; #pragma unroll
;                     for (int mi = 0; mi < 2; ++mi) o[mi] = MFMA32(load_nat(sS, STT, 32 * mi + r, 32 * ci + 16 * s + 8 * hh), vf[ci][s], o[mi]);
;         }
;         LDS_BARRIER();
;         const float cs = sCs[0];
;         if (CONS) {
;             __builtin_amdgcn_s_setprio(2);
;             if (seg) {
; #pragma unroll
;                 for (int mi = 0; mi < 2; ++mi)
; #pragma unroll
;                     for (int i = 0; i < 16; ++i) { const int il = 32 * mi + crow(i, hh); const unsigned off = (unsigned)sRow[il] * 1024u + (unsigned)(512 + h * 128 + 32 * wave + r);
;                         O[off] = f2bf(o[mi][i] * sRden[il]); }
;             }
	v_mov_b32_e32 v112, s14
	ds_read_b32 v114, v112 offset:2304
	s_waitcnt lgkmcnt(2)
	v_mfma_f32_32x32x16_bf16 v[64:79], v[108:111], v[100:103], v[64:79]
	v_perm_b32 v111, v163, v164, s39
	v_perm_b32 v110, v161, v162, s39
	v_perm_b32 v109, v159, v160, s39
	v_perm_b32 v108, v157, v158, s39
	s_nop 1
	v_mfma_f32_32x32x16_bf16 v[80:95], v[150:153], v[108:111], v[80:95]
	s_waitcnt lgkmcnt(1)
	v_mfma_f32_32x32x16_bf16 v[64:79], v[170:173], v[108:111], v[64:79]
	s_setprio 2
	s_cbranch_vccnz .LBB0_479
	ds_read_b128 v[150:153], v169 offset:1280
	ds_read_b128 v[154:157], v169 offset:1312
	ds_read_b128 v[158:161], v169 offset:1536
	v_or_b32_e32 v166, s24, v165
	ds_read_b128 v[162:165], v169 offset:1568
	s_waitcnt lgkmcnt(3)
	s_nop 1
	v_mul_f32_e32 v80, v80, v150
	v_mul_f32_e32 v81, v81, v151
	v_cvt_pk_bf16_f32 v170, v80, s0
	v_cvt_pk_bf16_f32 v171, v81, s0
	s_waitcnt lgkmcnt(1)
	v_lshl_add_u32 v80, v159, 10, v166
	v_lshl_add_u32 v112, v158, 10, v166
	v_mov_b32_e32 v81, v113
	v_lshl_add_u64 v[150:151], v[112:113], 1, s[12:13]
	v_lshl_add_u64 v[80:81], v[80:81], 1, s[12:13]
	global_store_short v[150:151], v170, off
	global_store_short v[80:81], v171, off
	v_mul_f32_e32 v80, v82, v152
	v_lshl_add_u32 v112, v160, 10, v166
	v_cvt_pk_bf16_f32 v81, v80, s0
	v_mul_f32_e32 v80, v83, v153
	v_lshl_add_u64 v[82:83], v[112:113], 1, s[12:13]
	v_cvt_pk_bf16_f32 v150, v80, s0
	v_lshl_add_u32 v80, v161, 10, v166
	global_store_short v[82:83], v81, off
	v_mov_b32_e32 v81, v113
	v_lshl_add_u64 v[80:81], v[80:81], 1, s[12:13]
	global_store_short v[80:81], v150, off
	v_mul_f32_e32 v80, v84, v154
	ds_read_b128 v[150:153], v169 offset:1600
	s_waitcnt lgkmcnt(1)
	v_lshl_add_u32 v112, v162, 10, v166
	v_cvt_pk_bf16_f32 v81, v80, s0
	v_mul_f32_e32 v80, v85, v155
	v_lshl_add_u64 v[82:83], v[112:113], 1, s[12:13]
	v_cvt_pk_bf16_f32 v84, v80, s0
	v_lshl_add_u32 v80, v163, 10, v166
	global_store_short v[82:83], v81, off
	v_mov_b32_e32 v81, v113
	v_lshl_add_u64 v[80:81], v[80:81], 1, s[12:13]
	global_store_short v[80:81], v84, off
	v_mul_f32_e32 v80, v86, v156
	v_cvt_pk_bf16_f32 v82, v80, s0
	v_mul_f32_e32 v80, v87, v157
	v_lshl_add_u32 v112, v164, 10, v166
	v_cvt_pk_bf16_f32 v86, v80, s0
	v_lshl_add_u64 v[80:81], v[112:113], 1, s[12:13]
	global_store_short v[80:81], v82, off
	ds_read_b128 v[80:83], v169 offset:1344
	v_lshl_add_u32 v84, v165, 10, v166
	v_mov_b32_e32 v85, v113
	v_lshl_add_u64 v[84:85], v[84:85], 1, s[12:13]
	global_store_short v[84:85], v86, off
	ds_read_b128 v[84:87], v169 offset:1376
	s_waitcnt lgkmcnt(1)
	v_mul_f32_e32 v80, v88, v80
	v_cvt_pk_bf16_f32 v158, v80, s0
	v_mul_f32_e32 v80, v89, v81
	v_cvt_pk_bf16_f32 v159, v80, s0
	v_lshl_add_u32 v80, v151, 10, v166
	v_lshl_add_u32 v112, v150, 10, v166
	v_mov_b32_e32 v81, v113
	ds_read_b128 v[154:157], v169 offset:1632
	v_lshl_add_u64 v[88:89], v[112:113], 1, s[12:13]
	v_lshl_add_u64 v[80:81], v[80:81], 1, s[12:13]
	global_store_short v[88:89], v158, off
	global_store_short v[80:81], v159, off
	v_mul_f32_e32 v80, v90, v82
	v_lshl_add_u32 v112, v152, 10, v166
	v_cvt_pk_bf16_f32 v81, v80, s0
	v_mul_f32_e32 v80, v91, v83
	v_lshl_add_u64 v[82:83], v[112:113], 1, s[12:13]
	v_cvt_pk_bf16_f32 v88, v80, s0
	v_lshl_add_u32 v80, v153, 10, v166
	global_store_short v[82:83], v81, off
	v_mov_b32_e32 v81, v113
	v_lshl_add_u64 v[80:81], v[80:81], 1, s[12:13]
	global_store_short v[80:81], v88, off
	s_waitcnt lgkmcnt(1)
	v_mul_f32_e32 v80, v92, v84
	ds_read_b128 v[88:91], v169 offset:1664
	s_waitcnt lgkmcnt(1)
	v_lshl_add_u32 v112, v154, 10, v166
	v_cvt_pk_bf16_f32 v81, v80, s0
	v_mul_f32_e32 v80, v93, v85
	v_lshl_add_u64 v[82:83], v[112:113], 1, s[12:13]
	v_cvt_pk_bf16_f32 v84, v80, s0
	v_lshl_add_u32 v80, v155, 10, v166
	global_store_short v[82:83], v81, off
	v_mov_b32_e32 v81, v113
	v_lshl_add_u64 v[80:81], v[80:81], 1, s[12:13]
	global_store_short v[80:81], v84, off
	v_mul_f32_e32 v80, v94, v86
	v_cvt_pk_bf16_f32 v82, v80, s0
	v_mul_f32_e32 v80, v95, v87
	v_lshl_add_u32 v112, v156, 10, v166
	v_cvt_pk_bf16_f32 v86, v80, s0
	v_lshl_add_u64 v[80:81], v[112:113], 1, s[12:13]
	global_store_short v[80:81], v82, off
	ds_read_b128 v[80:83], v169 offset:1408
	v_lshl_add_u32 v84, v157, 10, v166
	v_mov_b32_e32 v85, v113
	v_lshl_add_u64 v[84:85], v[84:85], 1, s[12:13]
	global_store_short v[84:85], v86, off
	ds_read_b128 v[84:87], v169 offset:1440
	s_waitcnt lgkmcnt(1)
; DI bf16_t f2bf(float a) { return (bf16_t)(pk2(a, 0.f) & 0xffffu); }
; DI int crow(int reg, int hh) { return (reg & 3) + 8 * (reg >> 2) + 4 * hh; }
; template <bool CONS>
; DI void ml_chain_role(const Params& p, unsigned char* smem, int dir, int b, int h) {
;     ...
;             if (seg) {
; #pragma unroll
;                 for (int mi = 0; mi < 2; ++mi)
; #pragma unroll
;                     for (int i = 0; i < 16; ++i) { const int il = 32 * mi + crow(i, hh); const unsigned off = (unsigned)sRow[il] * 1024u + (unsigned)(512 + h * 128 + 32 * wave + r);
;                         O[off] = f2bf(o[mi][i] * sRden[il]); }
;             }
	v_mul_f32_e32 v64, v64, v80
	v_cvt_pk_bf16_f32 v150, v64, s0
	v_mul_f32_e32 v64, v65, v81
	v_cvt_pk_bf16_f32 v151, v64, s0
	v_lshl_add_u32 v64, v89, 10, v166
	v_lshl_add_u32 v112, v88, 10, v166
	v_mov_b32_e32 v65, v113
	ds_read_b128 v[92:95], v169 offset:1696
	v_lshl_add_u64 v[80:81], v[112:113], 1, s[12:13]
	v_lshl_add_u64 v[64:65], v[64:65], 1, s[12:13]
	global_store_short v[80:81], v150, off
	global_store_short v[64:65], v151, off
	v_mul_f32_e32 v64, v66, v82
	v_lshl_add_u32 v112, v90, 10, v166
	v_cvt_pk_bf16_f32 v65, v64, s0
	v_mul_f32_e32 v64, v67, v83
	v_lshl_add_u64 v[66:67], v[112:113], 1, s[12:13]
	v_cvt_pk_bf16_f32 v80, v64, s0
	v_lshl_add_u32 v64, v91, 10, v166
	global_store_short v[66:67], v65, off
	v_mov_b32_e32 v65, v113
	v_lshl_add_u64 v[64:65], v[64:65], 1, s[12:13]
	global_store_short v[64:65], v80, off
	s_waitcnt lgkmcnt(1)
	v_mul_f32_e32 v64, v68, v84
	ds_read_b128 v[80:83], v169 offset:1728
	s_waitcnt lgkmcnt(1)
	v_lshl_add_u32 v112, v92, 10, v166
	v_cvt_pk_bf16_f32 v65, v64, s0
	v_mul_f32_e32 v64, v69, v85
	v_lshl_add_u64 v[66:67], v[112:113], 1, s[12:13]
	v_cvt_pk_bf16_f32 v68, v64, s0
	v_lshl_add_u32 v64, v93, 10, v166
	global_store_short v[66:67], v65, off
	v_mov_b32_e32 v65, v113
	v_lshl_add_u64 v[64:65], v[64:65], 1, s[12:13]
	global_store_short v[64:65], v68, off
	v_mul_f32_e32 v64, v70, v86
	v_cvt_pk_bf16_f32 v66, v64, s0
	v_mul_f32_e32 v64, v71, v87
	v_lshl_add_u32 v112, v94, 10, v166
	v_cvt_pk_bf16_f32 v70, v64, s0
	v_lshl_add_u64 v[64:65], v[112:113], 1, s[12:13]
	global_store_short v[64:65], v66, off
	ds_read_b128 v[64:67], v169 offset:1472
	v_lshl_add_u32 v68, v95, 10, v166
	v_mov_b32_e32 v69, v113
	v_lshl_add_u64 v[68:69], v[68:69], 1, s[12:13]
	global_store_short v[68:69], v70, off
	ds_read_b128 v[68:71], v169 offset:1504
	s_waitcnt lgkmcnt(1)
	v_mul_f32_e32 v64, v72, v64
	v_cvt_pk_bf16_f32 v88, v64, s0
	v_mul_f32_e32 v64, v73, v65
	v_cvt_pk_bf16_f32 v89, v64, s0
	v_lshl_add_u32 v64, v81, 10, v166
	v_lshl_add_u32 v112, v80, 10, v166
	v_mov_b32_e32 v65, v113
	ds_read_b128 v[84:87], v169 offset:1760
	v_lshl_add_u64 v[72:73], v[112:113], 1, s[12:13]
	v_lshl_add_u64 v[64:65], v[64:65], 1, s[12:13]
	global_store_short v[72:73], v88, off
	global_store_short v[64:65], v89, off
	v_mul_f32_e32 v64, v74, v66
	v_lshl_add_u32 v112, v82, 10, v166
	v_cvt_pk_bf16_f32 v65, v64, s0
	v_mul_f32_e32 v64, v75, v67
	v_lshl_add_u64 v[66:67], v[112:113], 1, s[12:13]
	v_cvt_pk_bf16_f32 v72, v64, s0
	v_lshl_add_u32 v64, v83, 10, v166
	global_store_short v[66:67], v65, off
	v_mov_b32_e32 v65, v113
	v_lshl_add_u64 v[64:65], v[64:65], 1, s[12:13]
	global_store_short v[64:65], v72, off
	s_waitcnt lgkmcnt(1)
	v_mul_f32_e32 v64, v76, v68
	s_waitcnt lgkmcnt(0)
	v_lshl_add_u32 v112, v84, 10, v166
	v_cvt_pk_bf16_f32 v65, v64, s0
	v_mul_f32_e32 v64, v77, v69
	v_lshl_add_u64 v[66:67], v[112:113], 1, s[12:13]
	v_cvt_pk_bf16_f32 v68, v64, s0
	v_lshl_add_u32 v64, v85, 10, v166
	global_store_short v[66:67], v65, off
	v_mov_b32_e32 v65, v113
	v_lshl_add_u64 v[64:65], v[64:65], 1, s[12:13]
	global_store_short v[64:65], v68, off
	v_mul_f32_e32 v64, v78, v70
	v_lshl_add_u32 v112, v86, 10, v166
	v_cvt_pk_bf16_f32 v65, v64, s0
	v_mul_f32_e32 v64, v79, v71
	v_lshl_add_u64 v[66:67], v[112:113], 1, s[12:13]
	v_cvt_pk_bf16_f32 v68, v64, s0
	v_lshl_add_u32 v64, v87, 10, v166
	global_store_short v[66:67], v65, off
	v_mov_b32_e32 v65, v113
	v_lshl_add_u64 v[64:65], v[64:65], 1, s[12:13]
	global_store_short v[64:65], v68, off
	s_branch .LBB0_479
